# P5: staged vmcnt waits between the passes (gate loads consumed group by group) and second-half gb loads hoisted to the epilogue top
# baseline (speedup 1.0000x reference)
.LBB0_1233:
	s_lshr_b32 s0, s20, 8
	v_lshl_or_b32 v207, s0, 6, v135
	v_lshl_or_b32 v137, v135, 6, v137
	v_lshlrev_b32_e32 v135, 2, v135
	s_lshl_b32 s0, s0, 13
	v_and_b32_e32 v135, 32, v135
	v_bitop3_b32 v209, v137, s0, v135 bitop3:0xde
	s_waitcnt vmcnt(28)
	v_cvt_f32_ubyte0_e32 v135, v202
	v_cvt_f32_ubyte1_e32 v137, v202
	v_cvt_f32_ubyte2_e32 v210, v202
	v_cvt_f32_ubyte3_e32 v202, v202
	v_mul_f32_e32 v213, 0x3b808081, v202
	v_cvt_f32_ubyte0_e32 v202, v203
	v_mul_f32_e32 v212, 0x3b808081, v210
	v_mul_f32_e32 v210, 0x3b808081, v202
	v_cvt_f32_ubyte1_e32 v202, v203
	v_mul_f32_e32 v135, 0x3b808081, v135
	v_mul_f32_e32 v211, 0x3b808081, v202
	v_cvt_f32_ubyte2_e32 v202, v203
	v_mul_f32_e32 v214, 0x3b808081, v202
	v_cvt_f32_ubyte3_e32 v202, v203
	v_max_f32_e32 v135, 0x3b008081, v135
	v_mul_f32_e32 v137, 0x3b808081, v137
	v_mul_f32_e32 v215, 0x3b808081, v202
	v_rcp_f32_e32 v202, v135
	v_max_f32_e32 v135, 0x3b008081, v210
	v_rcp_f32_e32 v210, v135
	v_max_f32_e32 v135, 0x3b008081, v137
	v_rcp_f32_e32 v203, v135
	v_max_f32_e32 v135, 0x3b008081, v211
	v_rcp_f32_e32 v211, v135
	v_max_f32_e32 v135, 0x3b008081, v212
	v_rcp_f32_e32 v212, v135
	v_max_f32_e32 v135, 0x3b008081, v214
	v_rcp_f32_e32 v214, v135
	v_max_f32_e32 v135, 0x3b008081, v213
	v_rcp_f32_e32 v213, v135
	s_lshr_b32 s0, s20, 1
	s_lshl_b32 s1, s20, 4
	s_and_b32 s21, s0, 0x60
	s_mov_b32 s0, 0x3b808081
	v_cvt_f32_ubyte3_e32 v219, v200
	v_cvt_f32_ubyte2_e32 v218, v200
	v_max_f32_e32 v135, 0x3b008081, v215
	v_cvt_f32_ubyte1_e32 v217, v200
	v_cvt_f32_ubyte0_e32 v216, v200
	v_pk_mul_f32 v[218:219], v[218:219], s[0:1] op_sel_hi:[1,0]
	v_rcp_f32_e32 v215, v135
	v_pk_mul_f32 v[216:217], v[216:217], s[0:1] op_sel_hi:[1,0]
	v_pk_mul_f32 v[212:213], v[218:219], v[212:213]
	v_pk_mul_f32 v[202:203], v[216:217], v[202:203]
	v_pk_mul_f32 v[68:69], v[68:69], v[212:213]
	v_cvt_f32_ubyte3_e32 v213, v201
	v_cvt_f32_ubyte2_e32 v212, v201
	v_pk_mul_f32 v[66:67], v[66:67], v[202:203]
	v_cvt_f32_ubyte1_e32 v203, v201
	v_cvt_f32_ubyte0_e32 v202, v201
	v_pk_mul_f32 v[200:201], v[212:213], s[0:1] op_sel_hi:[1,0]
	v_pk_mul_f32 v[202:203], v[202:203], s[0:1] op_sel_hi:[1,0]
	v_pk_mul_f32 v[200:201], v[200:201], v[214:215]
	v_pk_mul_f32 v[202:203], v[202:203], v[210:211]
	v_pk_mul_f32 v[76:77], v[76:77], v[200:201]
	v_cvt_f32_ubyte0_e32 v135, v198
	v_cvt_f32_ubyte1_e32 v137, v198
	v_cvt_f32_ubyte2_e32 v200, v198
	v_cvt_f32_ubyte3_e32 v198, v198
	v_pk_mul_f32 v[74:75], v[74:75], v[202:203]
	v_mul_f32_e32 v203, 0x3b808081, v198
	v_cvt_f32_ubyte0_e32 v198, v199
	v_mul_f32_e32 v202, 0x3b808081, v200
	v_mul_f32_e32 v200, 0x3b808081, v198
	v_cvt_f32_ubyte1_e32 v198, v199
	v_mul_f32_e32 v135, 0x3b808081, v135
	v_mul_f32_e32 v201, 0x3b808081, v198
	v_cvt_f32_ubyte2_e32 v198, v199
	v_mul_f32_e32 v210, 0x3b808081, v198
	v_cvt_f32_ubyte3_e32 v198, v199
	v_max_f32_e32 v135, 0x3b008081, v135
	v_mul_f32_e32 v137, 0x3b808081, v137
	v_mul_f32_e32 v211, 0x3b808081, v198
	v_rcp_f32_e32 v198, v135
	v_max_f32_e32 v135, 0x3b008081, v200
	v_rcp_f32_e32 v200, v135
	v_max_f32_e32 v135, 0x3b008081, v137
	v_rcp_f32_e32 v199, v135
	v_max_f32_e32 v135, 0x3b008081, v201
	v_rcp_f32_e32 v201, v135
	v_max_f32_e32 v135, 0x3b008081, v202
	v_rcp_f32_e32 v202, v135
	v_max_f32_e32 v135, 0x3b008081, v210
	v_rcp_f32_e32 v210, v135
	v_max_f32_e32 v135, 0x3b008081, v203
	v_rcp_f32_e32 v203, v135
	v_cvt_f32_ubyte3_e32 v215, v196
	v_cvt_f32_ubyte2_e32 v214, v196
	v_max_f32_e32 v135, 0x3b008081, v211
	v_cvt_f32_ubyte1_e32 v213, v196
	v_cvt_f32_ubyte0_e32 v212, v196
	v_pk_mul_f32 v[214:215], v[214:215], s[0:1] op_sel_hi:[1,0]
	v_rcp_f32_e32 v211, v135
	v_pk_mul_f32 v[212:213], v[212:213], s[0:1] op_sel_hi:[1,0]
	v_pk_mul_f32 v[202:203], v[214:215], v[202:203]
	v_pk_mul_f32 v[198:199], v[212:213], v[198:199]
	v_pk_mul_f32 v[80:81], v[80:81], v[202:203]
	v_cvt_f32_ubyte3_e32 v203, v197
	v_cvt_f32_ubyte2_e32 v202, v197
	v_pk_mul_f32 v[78:79], v[78:79], v[198:199]
	v_cvt_f32_ubyte1_e32 v199, v197
	v_cvt_f32_ubyte0_e32 v198, v197
	v_pk_mul_f32 v[196:197], v[202:203], s[0:1] op_sel_hi:[1,0]
	v_pk_mul_f32 v[198:199], v[198:199], s[0:1] op_sel_hi:[1,0]
	v_pk_mul_f32 v[196:197], v[196:197], v[210:211]
	v_pk_mul_f32 v[198:199], v[198:199], v[200:201]
	v_pk_mul_f32 v[88:89], v[88:89], v[196:197]
	s_waitcnt vmcnt(24)
	v_cvt_f32_ubyte0_e32 v135, v194
	v_cvt_f32_ubyte1_e32 v137, v194
	v_cvt_f32_ubyte2_e32 v196, v194
	v_cvt_f32_ubyte3_e32 v194, v194
	v_pk_mul_f32 v[86:87], v[86:87], v[198:199]
	v_mul_f32_e32 v199, 0x3b808081, v194
	v_cvt_f32_ubyte0_e32 v194, v195
	v_mul_f32_e32 v198, 0x3b808081, v196
	v_mul_f32_e32 v196, 0x3b808081, v194
	v_cvt_f32_ubyte1_e32 v194, v195
	v_mul_f32_e32 v135, 0x3b808081, v135
	v_mul_f32_e32 v197, 0x3b808081, v194
	v_cvt_f32_ubyte2_e32 v194, v195
	v_mul_f32_e32 v200, 0x3b808081, v194
	v_cvt_f32_ubyte3_e32 v194, v195
	v_max_f32_e32 v135, 0x3b008081, v135
	v_mul_f32_e32 v137, 0x3b808081, v137
	v_mul_f32_e32 v201, 0x3b808081, v194
	v_rcp_f32_e32 v194, v135
	v_max_f32_e32 v135, 0x3b008081, v196
	v_rcp_f32_e32 v196, v135
	v_max_f32_e32 v135, 0x3b008081, v137
	v_rcp_f32_e32 v195, v135
	v_max_f32_e32 v135, 0x3b008081, v197
	v_rcp_f32_e32 v197, v135
	v_max_f32_e32 v135, 0x3b008081, v198
	v_rcp_f32_e32 v198, v135
	v_max_f32_e32 v135, 0x3b008081, v200
	v_rcp_f32_e32 v200, v135
	v_max_f32_e32 v135, 0x3b008081, v199
	v_rcp_f32_e32 v199, v135
	v_cvt_f32_ubyte3_e32 v211, v192
	v_cvt_f32_ubyte2_e32 v210, v192
	v_max_f32_e32 v135, 0x3b008081, v201
	v_cvt_f32_ubyte1_e32 v203, v192
	v_cvt_f32_ubyte0_e32 v202, v192
	v_pk_mul_f32 v[210:211], v[210:211], s[0:1] op_sel_hi:[1,0]
	v_rcp_f32_e32 v201, v135
	v_pk_mul_f32 v[202:203], v[202:203], s[0:1] op_sel_hi:[1,0]
	v_pk_mul_f32 v[198:199], v[210:211], v[198:199]
	v_pk_mul_f32 v[194:195], v[202:203], v[194:195]
	v_pk_mul_f32 v[92:93], v[92:93], v[198:199]
	v_cvt_f32_ubyte3_e32 v199, v193
	v_cvt_f32_ubyte2_e32 v198, v193
	v_pk_mul_f32 v[90:91], v[90:91], v[194:195]
	v_cvt_f32_ubyte1_e32 v195, v193
	v_cvt_f32_ubyte0_e32 v194, v193
	v_pk_mul_f32 v[192:193], v[198:199], s[0:1] op_sel_hi:[1,0]
	v_pk_mul_f32 v[194:195], v[194:195], s[0:1] op_sel_hi:[1,0]
	v_pk_mul_f32 v[192:193], v[192:193], v[200:201]
	v_pk_mul_f32 v[194:195], v[194:195], v[196:197]
	v_pk_mul_f32 v[96:97], v[96:97], v[192:193]
	v_cvt_f32_ubyte0_e32 v135, v190
	v_cvt_f32_ubyte1_e32 v137, v190
	v_cvt_f32_ubyte2_e32 v192, v190
	v_cvt_f32_ubyte3_e32 v190, v190
	v_pk_mul_f32 v[94:95], v[94:95], v[194:195]
	v_mul_f32_e32 v195, 0x3b808081, v190
	v_cvt_f32_ubyte0_e32 v190, v191
	v_mul_f32_e32 v194, 0x3b808081, v192
	v_mul_f32_e32 v192, 0x3b808081, v190
	v_cvt_f32_ubyte1_e32 v190, v191
	v_mul_f32_e32 v135, 0x3b808081, v135
	v_mul_f32_e32 v193, 0x3b808081, v190
	v_cvt_f32_ubyte2_e32 v190, v191
	v_mul_f32_e32 v196, 0x3b808081, v190
	v_cvt_f32_ubyte3_e32 v190, v191
	v_max_f32_e32 v135, 0x3b008081, v135
	v_mul_f32_e32 v137, 0x3b808081, v137
	v_mul_f32_e32 v197, 0x3b808081, v190
	v_rcp_f32_e32 v190, v135
	v_max_f32_e32 v135, 0x3b008081, v192
	v_rcp_f32_e32 v192, v135
	v_max_f32_e32 v135, 0x3b008081, v137
	v_rcp_f32_e32 v191, v135
	v_max_f32_e32 v135, 0x3b008081, v193
	v_rcp_f32_e32 v193, v135
	v_max_f32_e32 v135, 0x3b008081, v194
	v_rcp_f32_e32 v194, v135
	v_max_f32_e32 v135, 0x3b008081, v196
	v_rcp_f32_e32 v196, v135
	v_max_f32_e32 v135, 0x3b008081, v195
	v_rcp_f32_e32 v195, v135
	v_cvt_f32_ubyte3_e32 v201, v188
	v_cvt_f32_ubyte2_e32 v200, v188
	v_max_f32_e32 v135, 0x3b008081, v197
	v_cvt_f32_ubyte1_e32 v199, v188
	v_cvt_f32_ubyte0_e32 v198, v188
	v_pk_mul_f32 v[200:201], v[200:201], s[0:1] op_sel_hi:[1,0]
	v_rcp_f32_e32 v197, v135
	v_pk_mul_f32 v[198:199], v[198:199], s[0:1] op_sel_hi:[1,0]
	v_pk_mul_f32 v[194:195], v[200:201], v[194:195]
	v_pk_mul_f32 v[190:191], v[198:199], v[190:191]
	v_pk_mul_f32 v[100:101], v[100:101], v[194:195]
	v_cvt_f32_ubyte3_e32 v195, v189
	v_cvt_f32_ubyte2_e32 v194, v189
	v_pk_mul_f32 v[98:99], v[98:99], v[190:191]
	v_cvt_f32_ubyte1_e32 v191, v189
	v_cvt_f32_ubyte0_e32 v190, v189
	v_pk_mul_f32 v[188:189], v[194:195], s[0:1] op_sel_hi:[1,0]
	v_pk_mul_f32 v[190:191], v[190:191], s[0:1] op_sel_hi:[1,0]
	v_pk_mul_f32 v[188:189], v[188:189], v[196:197]
	v_pk_mul_f32 v[190:191], v[190:191], v[192:193]
	v_pk_mul_f32 v[104:105], v[104:105], v[188:189]
	s_waitcnt vmcnt(20)
	v_cvt_f32_ubyte0_e32 v135, v186
	v_cvt_f32_ubyte1_e32 v137, v186
	v_cvt_f32_ubyte2_e32 v188, v186
	v_cvt_f32_ubyte3_e32 v186, v186
	v_pk_mul_f32 v[102:103], v[102:103], v[190:191]
	v_mul_f32_e32 v191, 0x3b808081, v186
	v_cvt_f32_ubyte0_e32 v186, v187
	v_mul_f32_e32 v190, 0x3b808081, v188
	v_mul_f32_e32 v188, 0x3b808081, v186
	v_cvt_f32_ubyte1_e32 v186, v187
	v_mul_f32_e32 v135, 0x3b808081, v135
	v_mul_f32_e32 v189, 0x3b808081, v186
	v_cvt_f32_ubyte2_e32 v186, v187
	v_mul_f32_e32 v192, 0x3b808081, v186
	v_cvt_f32_ubyte3_e32 v186, v187
	v_max_f32_e32 v135, 0x3b008081, v135
	v_mul_f32_e32 v137, 0x3b808081, v137
	v_mul_f32_e32 v193, 0x3b808081, v186
	v_rcp_f32_e32 v186, v135
	v_max_f32_e32 v135, 0x3b008081, v188
	v_rcp_f32_e32 v188, v135
	v_max_f32_e32 v135, 0x3b008081, v137
	v_rcp_f32_e32 v187, v135
	v_max_f32_e32 v135, 0x3b008081, v189
	v_rcp_f32_e32 v189, v135
	v_max_f32_e32 v135, 0x3b008081, v190
	v_rcp_f32_e32 v190, v135
	v_max_f32_e32 v135, 0x3b008081, v192
	v_rcp_f32_e32 v192, v135
	v_max_f32_e32 v135, 0x3b008081, v191
	v_rcp_f32_e32 v191, v135
	v_cvt_f32_ubyte3_e32 v197, v184
	v_cvt_f32_ubyte2_e32 v196, v184
	v_max_f32_e32 v135, 0x3b008081, v193
	v_cvt_f32_ubyte1_e32 v195, v184
	v_cvt_f32_ubyte0_e32 v194, v184
	v_pk_mul_f32 v[196:197], v[196:197], s[0:1] op_sel_hi:[1,0]
	v_rcp_f32_e32 v193, v135
	v_pk_mul_f32 v[194:195], v[194:195], s[0:1] op_sel_hi:[1,0]
	v_pk_mul_f32 v[190:191], v[196:197], v[190:191]
	v_pk_mul_f32 v[186:187], v[194:195], v[186:187]
	v_pk_mul_f32 v[112:113], v[112:113], v[190:191]
	v_cvt_f32_ubyte3_e32 v191, v185
	v_cvt_f32_ubyte2_e32 v190, v185
	v_pk_mul_f32 v[110:111], v[110:111], v[186:187]
	v_cvt_f32_ubyte1_e32 v187, v185
	v_cvt_f32_ubyte0_e32 v186, v185
	v_pk_mul_f32 v[184:185], v[190:191], s[0:1] op_sel_hi:[1,0]
	v_pk_mul_f32 v[186:187], v[186:187], s[0:1] op_sel_hi:[1,0]
	v_pk_mul_f32 v[184:185], v[184:185], v[192:193]
	v_pk_mul_f32 v[186:187], v[186:187], v[188:189]
	v_pk_mul_f32 v[120:121], v[120:121], v[184:185]
	v_cvt_f32_ubyte0_e32 v135, v182
	v_cvt_f32_ubyte1_e32 v137, v182
	v_cvt_f32_ubyte2_e32 v184, v182
	v_cvt_f32_ubyte3_e32 v182, v182
	v_pk_mul_f32 v[118:119], v[118:119], v[186:187]
	v_mul_f32_e32 v187, 0x3b808081, v182
	v_cvt_f32_ubyte0_e32 v182, v183
	v_mul_f32_e32 v186, 0x3b808081, v184
	v_mul_f32_e32 v184, 0x3b808081, v182
	v_cvt_f32_ubyte1_e32 v182, v183
	v_mul_f32_e32 v135, 0x3b808081, v135
	v_mul_f32_e32 v185, 0x3b808081, v182
	v_cvt_f32_ubyte2_e32 v182, v183
	v_mul_f32_e32 v188, 0x3b808081, v182
	v_cvt_f32_ubyte3_e32 v182, v183
	v_max_f32_e32 v135, 0x3b008081, v135
	v_mul_f32_e32 v137, 0x3b808081, v137
	v_mul_f32_e32 v189, 0x3b808081, v182
	v_rcp_f32_e32 v182, v135
	v_max_f32_e32 v135, 0x3b008081, v184
	v_rcp_f32_e32 v184, v135
	v_max_f32_e32 v135, 0x3b008081, v137
	v_rcp_f32_e32 v183, v135
	v_max_f32_e32 v135, 0x3b008081, v185
	v_rcp_f32_e32 v185, v135
	v_max_f32_e32 v135, 0x3b008081, v186
	v_rcp_f32_e32 v186, v135
	v_max_f32_e32 v135, 0x3b008081, v188
	v_rcp_f32_e32 v188, v135
	v_max_f32_e32 v135, 0x3b008081, v187
	v_rcp_f32_e32 v187, v135
	v_cvt_f32_ubyte3_e32 v193, v180
	v_cvt_f32_ubyte2_e32 v192, v180
	v_max_f32_e32 v135, 0x3b008081, v189
	v_cvt_f32_ubyte1_e32 v191, v180
	v_cvt_f32_ubyte0_e32 v190, v180
	v_pk_mul_f32 v[192:193], v[192:193], s[0:1] op_sel_hi:[1,0]
	v_rcp_f32_e32 v189, v135
	v_pk_mul_f32 v[190:191], v[190:191], s[0:1] op_sel_hi:[1,0]
	v_pk_mul_f32 v[186:187], v[192:193], v[186:187]
	v_pk_mul_f32 v[182:183], v[190:191], v[182:183]
	v_pk_mul_f32 v[124:125], v[124:125], v[186:187]
	v_cvt_f32_ubyte3_e32 v187, v181
	v_cvt_f32_ubyte2_e32 v186, v181
	v_pk_mul_f32 v[122:123], v[122:123], v[182:183]
	v_cvt_f32_ubyte1_e32 v183, v181
	v_cvt_f32_ubyte0_e32 v182, v181
	v_pk_mul_f32 v[180:181], v[186:187], s[0:1] op_sel_hi:[1,0]
	v_pk_mul_f32 v[182:183], v[182:183], s[0:1] op_sel_hi:[1,0]
	v_pk_mul_f32 v[180:181], v[180:181], v[188:189]
	v_pk_mul_f32 v[182:183], v[182:183], v[184:185]
	v_pk_mul_f32 v[128:129], v[128:129], v[180:181]
	s_waitcnt vmcnt(16)
	v_cvt_f32_ubyte0_e32 v135, v176
	v_cvt_f32_ubyte1_e32 v137, v176
	v_cvt_f32_ubyte2_e32 v180, v176
	v_cvt_f32_ubyte3_e32 v176, v176
	v_pk_mul_f32 v[126:127], v[126:127], v[182:183]
	v_mul_f32_e32 v183, 0x3b808081, v176
	v_cvt_f32_ubyte0_e32 v176, v177
	v_mul_f32_e32 v182, 0x3b808081, v180
	v_mul_f32_e32 v180, 0x3b808081, v176
	v_cvt_f32_ubyte1_e32 v176, v177
	v_mul_f32_e32 v135, 0x3b808081, v135
	v_mul_f32_e32 v181, 0x3b808081, v176
	v_cvt_f32_ubyte2_e32 v176, v177
	v_mul_f32_e32 v184, 0x3b808081, v176
	v_cvt_f32_ubyte3_e32 v176, v177
	v_max_f32_e32 v135, 0x3b008081, v135
	v_mul_f32_e32 v137, 0x3b808081, v137
	v_mul_f32_e32 v185, 0x3b808081, v176
	v_rcp_f32_e32 v176, v135
	v_max_f32_e32 v135, 0x3b008081, v180
	v_rcp_f32_e32 v180, v135
	v_max_f32_e32 v135, 0x3b008081, v137
	v_rcp_f32_e32 v177, v135
	v_max_f32_e32 v135, 0x3b008081, v181
	v_rcp_f32_e32 v181, v135
	v_max_f32_e32 v135, 0x3b008081, v182
	v_rcp_f32_e32 v182, v135
	v_max_f32_e32 v135, 0x3b008081, v184
	v_rcp_f32_e32 v184, v135
	v_max_f32_e32 v135, 0x3b008081, v183
	v_rcp_f32_e32 v183, v135
	v_cvt_f32_ubyte3_e32 v189, v174
	v_cvt_f32_ubyte2_e32 v188, v174
	v_max_f32_e32 v135, 0x3b008081, v185
	v_cvt_f32_ubyte1_e32 v187, v174
	v_cvt_f32_ubyte0_e32 v186, v174
	v_pk_mul_f32 v[188:189], v[188:189], s[0:1] op_sel_hi:[1,0]
	v_rcp_f32_e32 v185, v135
	v_pk_mul_f32 v[186:187], v[186:187], s[0:1] op_sel_hi:[1,0]
	v_pk_mul_f32 v[182:183], v[188:189], v[182:183]
	v_pk_mul_f32 v[176:177], v[186:187], v[176:177]
	v_pk_mul_f32 v[116:117], v[116:117], v[182:183]
	v_cvt_f32_ubyte3_e32 v183, v175
	v_cvt_f32_ubyte2_e32 v182, v175
	v_pk_mul_f32 v[114:115], v[114:115], v[176:177]
	v_cvt_f32_ubyte1_e32 v177, v175
	v_cvt_f32_ubyte0_e32 v176, v175
	v_pk_mul_f32 v[174:175], v[182:183], s[0:1] op_sel_hi:[1,0]
	v_pk_mul_f32 v[176:177], v[176:177], s[0:1] op_sel_hi:[1,0]
	v_pk_mul_f32 v[174:175], v[174:175], v[184:185]
	v_pk_mul_f32 v[176:177], v[176:177], v[180:181]
	v_pk_mul_f32 v[108:109], v[108:109], v[174:175]
	v_cvt_f32_ubyte0_e32 v135, v172
	v_cvt_f32_ubyte1_e32 v137, v172
	v_cvt_f32_ubyte2_e32 v174, v172
	v_cvt_f32_ubyte3_e32 v172, v172
	v_pk_mul_f32 v[106:107], v[106:107], v[176:177]
	v_mul_f32_e32 v177, 0x3b808081, v172
	v_cvt_f32_ubyte0_e32 v172, v173
	v_mul_f32_e32 v176, 0x3b808081, v174
	v_mul_f32_e32 v174, 0x3b808081, v172
	v_cvt_f32_ubyte1_e32 v172, v173
	v_mul_f32_e32 v135, 0x3b808081, v135
	v_mul_f32_e32 v175, 0x3b808081, v172
	v_cvt_f32_ubyte2_e32 v172, v173
	v_mul_f32_e32 v180, 0x3b808081, v172
	v_cvt_f32_ubyte3_e32 v172, v173
	v_max_f32_e32 v135, 0x3b008081, v135
	v_mul_f32_e32 v137, 0x3b808081, v137
	v_mul_f32_e32 v181, 0x3b808081, v172
	v_rcp_f32_e32 v172, v135
	v_max_f32_e32 v135, 0x3b008081, v174
	v_rcp_f32_e32 v174, v135
	v_max_f32_e32 v135, 0x3b008081, v137
	v_rcp_f32_e32 v173, v135
	v_max_f32_e32 v135, 0x3b008081, v175
	v_rcp_f32_e32 v175, v135
	v_max_f32_e32 v135, 0x3b008081, v176
	v_rcp_f32_e32 v176, v135
	v_max_f32_e32 v135, 0x3b008081, v180
	v_rcp_f32_e32 v180, v135
	v_max_f32_e32 v135, 0x3b008081, v177
	v_rcp_f32_e32 v177, v135
	v_cvt_f32_ubyte3_e32 v185, v170
	v_cvt_f32_ubyte2_e32 v184, v170
	v_max_f32_e32 v135, 0x3b008081, v181
	v_cvt_f32_ubyte1_e32 v183, v170
	v_cvt_f32_ubyte0_e32 v182, v170
	v_pk_mul_f32 v[184:185], v[184:185], s[0:1] op_sel_hi:[1,0]
	v_rcp_f32_e32 v181, v135
	v_pk_mul_f32 v[182:183], v[182:183], s[0:1] op_sel_hi:[1,0]
	v_pk_mul_f32 v[176:177], v[184:185], v[176:177]
	v_pk_mul_f32 v[172:173], v[182:183], v[172:173]
	v_pk_mul_f32 v[84:85], v[84:85], v[176:177]
	v_cvt_f32_ubyte3_e32 v177, v171
	v_cvt_f32_ubyte2_e32 v176, v171
	v_pk_mul_f32 v[82:83], v[82:83], v[172:173]
	v_cvt_f32_ubyte1_e32 v173, v171
	v_cvt_f32_ubyte0_e32 v172, v171
	v_pk_mul_f32 v[170:171], v[176:177], s[0:1] op_sel_hi:[1,0]
	v_pk_mul_f32 v[172:173], v[172:173], s[0:1] op_sel_hi:[1,0]
	v_pk_mul_f32 v[170:171], v[170:171], v[180:181]
	v_pk_mul_f32 v[172:173], v[172:173], v[174:175]
	v_pk_mul_f32 v[72:73], v[72:73], v[170:171]
	s_waitcnt vmcnt(12)
	v_cvt_f32_ubyte0_e32 v135, v168
	v_cvt_f32_ubyte1_e32 v137, v168
	v_cvt_f32_ubyte2_e32 v170, v168
	v_cvt_f32_ubyte3_e32 v168, v168
	v_pk_mul_f32 v[70:71], v[70:71], v[172:173]
	v_mul_f32_e32 v173, 0x3b808081, v168
	v_cvt_f32_ubyte0_e32 v168, v169
	v_mul_f32_e32 v172, 0x3b808081, v170
	v_mul_f32_e32 v170, 0x3b808081, v168
	v_cvt_f32_ubyte1_e32 v168, v169
	v_mul_f32_e32 v135, 0x3b808081, v135
	v_mul_f32_e32 v171, 0x3b808081, v168
	v_cvt_f32_ubyte2_e32 v168, v169
	v_mul_f32_e32 v174, 0x3b808081, v168
	v_cvt_f32_ubyte3_e32 v168, v169
	v_max_f32_e32 v135, 0x3b008081, v135
	v_mul_f32_e32 v137, 0x3b808081, v137
	v_mul_f32_e32 v175, 0x3b808081, v168
	v_rcp_f32_e32 v168, v135
	v_max_f32_e32 v135, 0x3b008081, v170
	v_rcp_f32_e32 v170, v135
	v_max_f32_e32 v135, 0x3b008081, v137
	v_rcp_f32_e32 v169, v135
	v_max_f32_e32 v135, 0x3b008081, v171
	v_rcp_f32_e32 v171, v135
	v_max_f32_e32 v135, 0x3b008081, v172
	v_rcp_f32_e32 v172, v135
	v_max_f32_e32 v135, 0x3b008081, v174
	v_rcp_f32_e32 v174, v135
	v_max_f32_e32 v135, 0x3b008081, v173
	v_rcp_f32_e32 v173, v135
	v_cvt_f32_ubyte3_e32 v181, v166
	v_cvt_f32_ubyte2_e32 v180, v166
	v_max_f32_e32 v135, 0x3b008081, v175
	v_cvt_f32_ubyte1_e32 v177, v166
	v_cvt_f32_ubyte0_e32 v176, v166
	v_pk_mul_f32 v[180:181], v[180:181], s[0:1] op_sel_hi:[1,0]
	v_rcp_f32_e32 v175, v135
	v_pk_mul_f32 v[176:177], v[176:177], s[0:1] op_sel_hi:[1,0]
	v_pk_mul_f32 v[172:173], v[180:181], v[172:173]
	v_pk_mul_f32 v[168:169], v[176:177], v[168:169]
	v_pk_mul_f32 v[64:65], v[64:65], v[172:173]
	v_cvt_f32_ubyte3_e32 v173, v167
	v_cvt_f32_ubyte2_e32 v172, v167
	v_pk_mul_f32 v[62:63], v[62:63], v[168:169]
	v_cvt_f32_ubyte1_e32 v169, v167
	v_cvt_f32_ubyte0_e32 v168, v167
	v_pk_mul_f32 v[166:167], v[172:173], s[0:1] op_sel_hi:[1,0]
	v_pk_mul_f32 v[168:169], v[168:169], s[0:1] op_sel_hi:[1,0]
	v_pk_mul_f32 v[166:167], v[166:167], v[174:175]
	v_pk_mul_f32 v[168:169], v[168:169], v[170:171]
	v_pk_mul_f32 v[60:61], v[60:61], v[166:167]
	v_cvt_f32_ubyte0_e32 v135, v164
	v_cvt_f32_ubyte1_e32 v137, v164
	v_cvt_f32_ubyte2_e32 v166, v164
	v_cvt_f32_ubyte3_e32 v164, v164
	v_pk_mul_f32 v[58:59], v[58:59], v[168:169]
	v_mul_f32_e32 v169, 0x3b808081, v164
	v_cvt_f32_ubyte0_e32 v164, v165
	v_mul_f32_e32 v168, 0x3b808081, v166
	v_mul_f32_e32 v166, 0x3b808081, v164
	v_cvt_f32_ubyte1_e32 v164, v165
	v_mul_f32_e32 v135, 0x3b808081, v135
	v_mul_f32_e32 v167, 0x3b808081, v164
	v_cvt_f32_ubyte2_e32 v164, v165
	v_mul_f32_e32 v170, 0x3b808081, v164
	v_cvt_f32_ubyte3_e32 v164, v165
	v_max_f32_e32 v135, 0x3b008081, v135
	v_mul_f32_e32 v137, 0x3b808081, v137
	v_mul_f32_e32 v171, 0x3b808081, v164
	v_rcp_f32_e32 v164, v135
	v_max_f32_e32 v135, 0x3b008081, v166
	v_rcp_f32_e32 v166, v135
	v_max_f32_e32 v135, 0x3b008081, v137
	v_rcp_f32_e32 v165, v135
	v_max_f32_e32 v135, 0x3b008081, v167
	v_rcp_f32_e32 v167, v135
	v_max_f32_e32 v135, 0x3b008081, v168
	v_rcp_f32_e32 v168, v135
	v_max_f32_e32 v135, 0x3b008081, v170
	v_rcp_f32_e32 v170, v135
	v_max_f32_e32 v135, 0x3b008081, v169
	v_rcp_f32_e32 v169, v135
	v_cvt_f32_ubyte3_e32 v175, v162
	v_cvt_f32_ubyte2_e32 v174, v162
	v_max_f32_e32 v135, 0x3b008081, v171
	v_cvt_f32_ubyte1_e32 v173, v162
	v_cvt_f32_ubyte0_e32 v172, v162
	v_pk_mul_f32 v[174:175], v[174:175], s[0:1] op_sel_hi:[1,0]
	v_rcp_f32_e32 v171, v135
	v_pk_mul_f32 v[172:173], v[172:173], s[0:1] op_sel_hi:[1,0]
	v_pk_mul_f32 v[168:169], v[174:175], v[168:169]
	v_pk_mul_f32 v[164:165], v[172:173], v[164:165]
	v_pk_mul_f32 v[56:57], v[56:57], v[168:169]
	v_cvt_f32_ubyte3_e32 v169, v163
	v_cvt_f32_ubyte2_e32 v168, v163
	v_pk_mul_f32 v[54:55], v[54:55], v[164:165]
	v_cvt_f32_ubyte1_e32 v165, v163
	v_cvt_f32_ubyte0_e32 v164, v163
	v_pk_mul_f32 v[162:163], v[168:169], s[0:1] op_sel_hi:[1,0]
	v_pk_mul_f32 v[164:165], v[164:165], s[0:1] op_sel_hi:[1,0]
	v_pk_mul_f32 v[162:163], v[162:163], v[170:171]
	v_pk_mul_f32 v[164:165], v[164:165], v[166:167]
	v_pk_mul_f32 v[52:53], v[52:53], v[162:163]
	s_waitcnt vmcnt(8)
	v_cvt_f32_ubyte0_e32 v135, v160
	v_cvt_f32_ubyte1_e32 v137, v160
	v_cvt_f32_ubyte2_e32 v162, v160
	v_cvt_f32_ubyte3_e32 v160, v160
	v_pk_mul_f32 v[50:51], v[50:51], v[164:165]
	v_mul_f32_e32 v165, 0x3b808081, v160
	v_cvt_f32_ubyte0_e32 v160, v161
	v_mul_f32_e32 v164, 0x3b808081, v162
	v_mul_f32_e32 v162, 0x3b808081, v160
	v_cvt_f32_ubyte1_e32 v160, v161
	v_mul_f32_e32 v135, 0x3b808081, v135
	v_mul_f32_e32 v163, 0x3b808081, v160
	v_cvt_f32_ubyte2_e32 v160, v161
	v_mul_f32_e32 v166, 0x3b808081, v160
	v_cvt_f32_ubyte3_e32 v160, v161
	v_max_f32_e32 v135, 0x3b008081, v135
	v_mul_f32_e32 v137, 0x3b808081, v137
	v_mul_f32_e32 v167, 0x3b808081, v160
	v_rcp_f32_e32 v160, v135
	v_max_f32_e32 v135, 0x3b008081, v162
	v_rcp_f32_e32 v162, v135
	v_max_f32_e32 v135, 0x3b008081, v137
	v_rcp_f32_e32 v161, v135
	v_max_f32_e32 v135, 0x3b008081, v163
	v_rcp_f32_e32 v163, v135
	v_max_f32_e32 v135, 0x3b008081, v164
	v_rcp_f32_e32 v164, v135
	v_max_f32_e32 v135, 0x3b008081, v166
	v_rcp_f32_e32 v166, v135
	v_max_f32_e32 v135, 0x3b008081, v165
	v_rcp_f32_e32 v165, v135
	v_cvt_f32_ubyte3_e32 v171, v158
	v_cvt_f32_ubyte2_e32 v170, v158
	v_max_f32_e32 v135, 0x3b008081, v167
	v_cvt_f32_ubyte1_e32 v169, v158
	v_cvt_f32_ubyte0_e32 v168, v158
	v_pk_mul_f32 v[170:171], v[170:171], s[0:1] op_sel_hi:[1,0]
	v_rcp_f32_e32 v167, v135
	v_pk_mul_f32 v[168:169], v[168:169], s[0:1] op_sel_hi:[1,0]
	v_pk_mul_f32 v[164:165], v[170:171], v[164:165]
	v_pk_mul_f32 v[160:161], v[168:169], v[160:161]
	v_pk_mul_f32 v[48:49], v[48:49], v[164:165]
	v_cvt_f32_ubyte3_e32 v165, v159
	v_cvt_f32_ubyte2_e32 v164, v159
	v_pk_mul_f32 v[46:47], v[46:47], v[160:161]
	v_cvt_f32_ubyte1_e32 v161, v159
	v_cvt_f32_ubyte0_e32 v160, v159
	v_pk_mul_f32 v[158:159], v[164:165], s[0:1] op_sel_hi:[1,0]
	v_pk_mul_f32 v[160:161], v[160:161], s[0:1] op_sel_hi:[1,0]
	v_pk_mul_f32 v[158:159], v[158:159], v[166:167]
	v_pk_mul_f32 v[160:161], v[160:161], v[162:163]
	v_pk_mul_f32 v[44:45], v[44:45], v[158:159]
	v_cvt_f32_ubyte0_e32 v135, v156
	v_cvt_f32_ubyte1_e32 v137, v156
	v_cvt_f32_ubyte2_e32 v158, v156
	v_cvt_f32_ubyte3_e32 v156, v156
	v_pk_mul_f32 v[42:43], v[42:43], v[160:161]
	v_mul_f32_e32 v161, 0x3b808081, v156
	v_cvt_f32_ubyte0_e32 v156, v157
	v_mul_f32_e32 v160, 0x3b808081, v158
	v_mul_f32_e32 v158, 0x3b808081, v156
	v_cvt_f32_ubyte1_e32 v156, v157
	v_mul_f32_e32 v135, 0x3b808081, v135
	v_mul_f32_e32 v159, 0x3b808081, v156
	v_cvt_f32_ubyte2_e32 v156, v157
	v_mul_f32_e32 v162, 0x3b808081, v156
	v_cvt_f32_ubyte3_e32 v156, v157
	v_max_f32_e32 v135, 0x3b008081, v135
	v_mul_f32_e32 v137, 0x3b808081, v137
	v_mul_f32_e32 v163, 0x3b808081, v156
	v_rcp_f32_e32 v156, v135
	v_max_f32_e32 v135, 0x3b008081, v158
	v_rcp_f32_e32 v158, v135
	v_max_f32_e32 v135, 0x3b008081, v137
	v_rcp_f32_e32 v157, v135
	v_max_f32_e32 v135, 0x3b008081, v159
	v_rcp_f32_e32 v159, v135
	v_max_f32_e32 v135, 0x3b008081, v160
	v_rcp_f32_e32 v160, v135
	v_max_f32_e32 v135, 0x3b008081, v162
	v_rcp_f32_e32 v162, v135
	v_max_f32_e32 v135, 0x3b008081, v161
	v_rcp_f32_e32 v161, v135
	v_cvt_f32_ubyte3_e32 v167, v154
	v_cvt_f32_ubyte2_e32 v166, v154
	v_max_f32_e32 v135, 0x3b008081, v163
	v_cvt_f32_ubyte1_e32 v165, v154
	v_cvt_f32_ubyte0_e32 v164, v154
	v_pk_mul_f32 v[166:167], v[166:167], s[0:1] op_sel_hi:[1,0]
	v_rcp_f32_e32 v163, v135
	v_pk_mul_f32 v[164:165], v[164:165], s[0:1] op_sel_hi:[1,0]
	v_pk_mul_f32 v[160:161], v[166:167], v[160:161]
	v_pk_mul_f32 v[156:157], v[164:165], v[156:157]
	v_pk_mul_f32 v[40:41], v[40:41], v[160:161]
	v_cvt_f32_ubyte3_e32 v161, v155
	v_cvt_f32_ubyte2_e32 v160, v155
	v_pk_mul_f32 v[38:39], v[38:39], v[156:157]
	v_cvt_f32_ubyte1_e32 v157, v155
	v_cvt_f32_ubyte0_e32 v156, v155
	v_pk_mul_f32 v[154:155], v[160:161], s[0:1] op_sel_hi:[1,0]
	v_pk_mul_f32 v[156:157], v[156:157], s[0:1] op_sel_hi:[1,0]
	v_pk_mul_f32 v[154:155], v[154:155], v[162:163]
	v_pk_mul_f32 v[156:157], v[156:157], v[158:159]
	v_pk_mul_f32 v[36:37], v[36:37], v[154:155]
	s_waitcnt vmcnt(4)
	v_cvt_f32_ubyte0_e32 v135, v152
	v_cvt_f32_ubyte1_e32 v137, v152
	v_cvt_f32_ubyte2_e32 v154, v152
	v_cvt_f32_ubyte3_e32 v152, v152
	v_pk_mul_f32 v[34:35], v[34:35], v[156:157]
	v_mul_f32_e32 v157, 0x3b808081, v152
	v_cvt_f32_ubyte0_e32 v152, v153
	v_mul_f32_e32 v156, 0x3b808081, v154
	v_mul_f32_e32 v154, 0x3b808081, v152
	v_cvt_f32_ubyte1_e32 v152, v153
	v_mul_f32_e32 v135, 0x3b808081, v135
	v_mul_f32_e32 v155, 0x3b808081, v152
	v_cvt_f32_ubyte2_e32 v152, v153
	v_mul_f32_e32 v158, 0x3b808081, v152
	v_cvt_f32_ubyte3_e32 v152, v153
	v_max_f32_e32 v135, 0x3b008081, v135
	v_mul_f32_e32 v137, 0x3b808081, v137
	v_mul_f32_e32 v159, 0x3b808081, v152
	v_rcp_f32_e32 v152, v135
	v_max_f32_e32 v135, 0x3b008081, v154
	v_rcp_f32_e32 v154, v135
	v_max_f32_e32 v135, 0x3b008081, v137
	v_rcp_f32_e32 v153, v135
	v_max_f32_e32 v135, 0x3b008081, v155
	v_rcp_f32_e32 v155, v135
	v_max_f32_e32 v135, 0x3b008081, v156
	v_rcp_f32_e32 v156, v135
	v_max_f32_e32 v135, 0x3b008081, v158
	v_rcp_f32_e32 v158, v135
	v_max_f32_e32 v135, 0x3b008081, v157
	v_rcp_f32_e32 v157, v135
	v_cvt_f32_ubyte3_e32 v163, v150
	v_cvt_f32_ubyte2_e32 v162, v150
	v_max_f32_e32 v135, 0x3b008081, v159
	v_cvt_f32_ubyte1_e32 v161, v150
	v_cvt_f32_ubyte0_e32 v160, v150
	v_pk_mul_f32 v[162:163], v[162:163], s[0:1] op_sel_hi:[1,0]
	v_rcp_f32_e32 v159, v135
	v_pk_mul_f32 v[160:161], v[160:161], s[0:1] op_sel_hi:[1,0]
	v_pk_mul_f32 v[156:157], v[162:163], v[156:157]
	v_pk_mul_f32 v[152:153], v[160:161], v[152:153]
	v_pk_mul_f32 v[28:29], v[28:29], v[156:157]
	v_cvt_f32_ubyte3_e32 v157, v151
	v_cvt_f32_ubyte2_e32 v156, v151
	v_pk_mul_f32 v[26:27], v[26:27], v[152:153]
	v_cvt_f32_ubyte1_e32 v153, v151
	v_cvt_f32_ubyte0_e32 v152, v151
	v_pk_mul_f32 v[150:151], v[156:157], s[0:1] op_sel_hi:[1,0]
	v_pk_mul_f32 v[152:153], v[152:153], s[0:1] op_sel_hi:[1,0]
	v_pk_mul_f32 v[150:151], v[150:151], v[158:159]
	v_pk_mul_f32 v[152:153], v[152:153], v[154:155]
	v_pk_mul_f32 v[20:21], v[20:21], v[150:151]
	v_cvt_f32_ubyte0_e32 v135, v148
	v_cvt_f32_ubyte1_e32 v137, v148
	v_cvt_f32_ubyte2_e32 v150, v148
	v_cvt_f32_ubyte3_e32 v148, v148
	v_pk_mul_f32 v[18:19], v[18:19], v[152:153]
	v_mul_f32_e32 v153, 0x3b808081, v148
	v_cvt_f32_ubyte0_e32 v148, v149
	v_mul_f32_e32 v152, 0x3b808081, v150
	v_mul_f32_e32 v150, 0x3b808081, v148
	v_cvt_f32_ubyte1_e32 v148, v149
	v_mul_f32_e32 v135, 0x3b808081, v135
	v_mul_f32_e32 v151, 0x3b808081, v148
	v_cvt_f32_ubyte2_e32 v148, v149
	v_mul_f32_e32 v154, 0x3b808081, v148
	v_cvt_f32_ubyte3_e32 v148, v149
	v_max_f32_e32 v135, 0x3b008081, v135
	v_mul_f32_e32 v137, 0x3b808081, v137
	v_mul_f32_e32 v155, 0x3b808081, v148
	v_rcp_f32_e32 v148, v135
	v_max_f32_e32 v135, 0x3b008081, v150
	v_rcp_f32_e32 v150, v135
	v_max_f32_e32 v135, 0x3b008081, v137
	v_rcp_f32_e32 v149, v135
	v_max_f32_e32 v135, 0x3b008081, v151
	v_rcp_f32_e32 v151, v135
	v_max_f32_e32 v135, 0x3b008081, v152
	v_rcp_f32_e32 v152, v135
	v_max_f32_e32 v135, 0x3b008081, v154
	v_rcp_f32_e32 v154, v135
	v_max_f32_e32 v135, 0x3b008081, v153
	v_rcp_f32_e32 v153, v135
	v_cvt_f32_ubyte3_e32 v159, v146
	v_cvt_f32_ubyte2_e32 v158, v146
	v_max_f32_e32 v135, 0x3b008081, v155
	v_cvt_f32_ubyte1_e32 v157, v146
	v_cvt_f32_ubyte0_e32 v156, v146
	v_pk_mul_f32 v[158:159], v[158:159], s[0:1] op_sel_hi:[1,0]
	v_rcp_f32_e32 v155, v135
	v_pk_mul_f32 v[156:157], v[156:157], s[0:1] op_sel_hi:[1,0]
	v_pk_mul_f32 v[152:153], v[158:159], v[152:153]
	v_pk_mul_f32 v[148:149], v[156:157], v[148:149]
	v_pk_mul_f32 v[32:33], v[32:33], v[152:153]
	v_cvt_f32_ubyte3_e32 v153, v147
	v_cvt_f32_ubyte2_e32 v152, v147
	v_pk_mul_f32 v[30:31], v[30:31], v[148:149]
	v_cvt_f32_ubyte1_e32 v149, v147
	v_cvt_f32_ubyte0_e32 v148, v147
	v_pk_mul_f32 v[146:147], v[152:153], s[0:1] op_sel_hi:[1,0]
	v_pk_mul_f32 v[148:149], v[148:149], s[0:1] op_sel_hi:[1,0]
	v_pk_mul_f32 v[146:147], v[146:147], v[154:155]
	v_pk_mul_f32 v[148:149], v[148:149], v[150:151]
	v_pk_mul_f32 v[24:25], v[24:25], v[146:147]
	s_waitcnt vmcnt(0)
	v_cvt_f32_ubyte0_e32 v135, v144
	v_cvt_f32_ubyte1_e32 v137, v144
	v_cvt_f32_ubyte2_e32 v146, v144
	v_cvt_f32_ubyte3_e32 v144, v144
	v_pk_mul_f32 v[22:23], v[22:23], v[148:149]
	v_mul_f32_e32 v149, 0x3b808081, v144
	v_cvt_f32_ubyte0_e32 v144, v145
	v_mul_f32_e32 v148, 0x3b808081, v146
	v_mul_f32_e32 v146, 0x3b808081, v144
	v_cvt_f32_ubyte1_e32 v144, v145
	v_mul_f32_e32 v135, 0x3b808081, v135
	v_mul_f32_e32 v147, 0x3b808081, v144
	v_cvt_f32_ubyte2_e32 v144, v145
	v_mul_f32_e32 v150, 0x3b808081, v144
	v_cvt_f32_ubyte3_e32 v144, v145
	v_max_f32_e32 v135, 0x3b008081, v135
	v_mul_f32_e32 v137, 0x3b808081, v137
	v_mul_f32_e32 v151, 0x3b808081, v144
	v_rcp_f32_e32 v144, v135
	v_max_f32_e32 v135, 0x3b008081, v146
	v_rcp_f32_e32 v146, v135
	v_max_f32_e32 v135, 0x3b008081, v137
	v_rcp_f32_e32 v145, v135
	v_max_f32_e32 v135, 0x3b008081, v147
	v_rcp_f32_e32 v147, v135
	v_max_f32_e32 v135, 0x3b008081, v148
	v_rcp_f32_e32 v148, v135
	v_max_f32_e32 v135, 0x3b008081, v150
	v_rcp_f32_e32 v150, v135
	v_max_f32_e32 v135, 0x3b008081, v149
	v_rcp_f32_e32 v149, v135
	v_cvt_f32_ubyte3_e32 v155, v142
	v_cvt_f32_ubyte2_e32 v154, v142
	v_max_f32_e32 v135, 0x3b008081, v151
	v_cvt_f32_ubyte1_e32 v153, v142
	v_cvt_f32_ubyte0_e32 v152, v142
	v_pk_mul_f32 v[154:155], v[154:155], s[0:1] op_sel_hi:[1,0]
	v_rcp_f32_e32 v151, v135
	v_pk_mul_f32 v[152:153], v[152:153], s[0:1] op_sel_hi:[1,0]
	v_pk_mul_f32 v[148:149], v[154:155], v[148:149]
	v_pk_mul_f32 v[144:145], v[152:153], v[144:145]
	v_pk_mul_f32 v[12:13], v[12:13], v[148:149]
	v_cvt_f32_ubyte3_e32 v149, v143
	v_cvt_f32_ubyte2_e32 v148, v143
	v_pk_mul_f32 v[10:11], v[10:11], v[144:145]
	v_cvt_f32_ubyte1_e32 v145, v143
	v_cvt_f32_ubyte0_e32 v144, v143
	v_pk_mul_f32 v[142:143], v[148:149], s[0:1] op_sel_hi:[1,0]
	v_pk_mul_f32 v[144:145], v[144:145], s[0:1] op_sel_hi:[1,0]
	v_pk_mul_f32 v[142:143], v[142:143], v[150:151]
	v_pk_mul_f32 v[144:145], v[144:145], v[146:147]
	v_pk_mul_f32 v[4:5], v[4:5], v[142:143]
	v_cvt_f32_ubyte0_e32 v135, v140
	v_cvt_f32_ubyte1_e32 v137, v140
	v_cvt_f32_ubyte2_e32 v142, v140
	v_cvt_f32_ubyte3_e32 v140, v140
	v_pk_mul_f32 v[2:3], v[2:3], v[144:145]
	v_mul_f32_e32 v145, 0x3b808081, v140
	v_cvt_f32_ubyte0_e32 v140, v141
	v_mul_f32_e32 v144, 0x3b808081, v142
	v_mul_f32_e32 v142, 0x3b808081, v140
	v_cvt_f32_ubyte1_e32 v140, v141
	v_mul_f32_e32 v135, 0x3b808081, v135
	v_mul_f32_e32 v143, 0x3b808081, v140
	v_cvt_f32_ubyte2_e32 v140, v141
	v_mul_f32_e32 v146, 0x3b808081, v140
	v_cvt_f32_ubyte3_e32 v140, v141
	v_max_f32_e32 v135, 0x3b008081, v135
	v_mul_f32_e32 v137, 0x3b808081, v137
	v_mul_f32_e32 v147, 0x3b808081, v140
	v_rcp_f32_e32 v140, v135
	v_max_f32_e32 v135, 0x3b008081, v142
	v_rcp_f32_e32 v142, v135
	v_max_f32_e32 v135, 0x3b008081, v137
	v_rcp_f32_e32 v141, v135
	v_max_f32_e32 v135, 0x3b008081, v143
	v_rcp_f32_e32 v143, v135
	v_max_f32_e32 v135, 0x3b008081, v144
	v_rcp_f32_e32 v144, v135
	v_max_f32_e32 v135, 0x3b008081, v146
	v_rcp_f32_e32 v146, v135
	v_max_f32_e32 v135, 0x3b008081, v145
	v_rcp_f32_e32 v145, v135
	v_cvt_f32_ubyte1_e32 v149, v138
	v_cvt_f32_ubyte0_e32 v148, v138
	v_cvt_f32_ubyte3_e32 v151, v138
	v_cvt_f32_ubyte2_e32 v150, v138
	v_pk_mul_f32 v[150:151], v[150:151], s[0:1] op_sel_hi:[1,0]
	v_pk_mul_f32 v[148:149], v[148:149], s[0:1] op_sel_hi:[1,0]
	v_pk_mul_f32 v[144:145], v[150:151], v[144:145]
	v_pk_mul_f32 v[140:141], v[148:149], v[140:141]
	v_pk_mul_f32 v[16:17], v[16:17], v[144:145]
	v_pk_mul_f32 v[14:15], v[14:15], v[140:141]
	v_cvt_f32_ubyte1_e32 v141, v139
	v_cvt_f32_ubyte0_e32 v140, v139
	v_cvt_f32_ubyte3_e32 v145, v139
	v_cvt_f32_ubyte2_e32 v144, v139
	v_pk_mul_f32 v[138:139], v[144:145], s[0:1] op_sel_hi:[1,0]
	v_pk_mul_f32 v[140:141], v[140:141], s[0:1] op_sel_hi:[1,0]
	s_add_i32 s0, s8, s30
	s_and_b32 s16, s1, 0xfffffc00
	s_ashr_i32 s1, s0, 31
	s_lshr_b32 s1, s1, 27
	s_add_i32 s1, s0, s1
	s_ashr_i32 s8, s1, 5
	s_lshl_b32 s8, s8, 3
	s_sub_i32 s9, 64, s8
	s_min_i32 s9, s9, 8
	v_max_f32_e32 v135, 0x3b008081, v147
	s_abs_i32 s10, s9
	v_rcp_f32_e32 v147, v135
	v_cvt_f32_u32_e32 v135, s10
	s_sub_i32 s12, 0, s10
	s_andn2_b32 s1, s1, 31
	s_sub_i32 s1, s0, s1
	v_rcp_iflag_f32_e32 v135, v135
	s_abs_i32 s11, s1
	s_xor_b32 s0, s1, s9
	s_ashr_i32 s0, s0, 31
	v_mul_f32_e32 v135, 0x4f7ffffe, v135
	v_cvt_u32_f32_e32 v135, v135
	v_pk_mul_f32 v[140:141], v[140:141], v[142:143]
	v_pk_mul_f32 v[138:139], v[138:139], v[146:147]
	v_pk_mul_f32 v[6:7], v[6:7], v[140:141]
	v_readfirstlane_b32 s13, v135
	s_mul_i32 s12, s12, s13
	s_mul_hi_u32 s12, s13, s12
	s_add_i32 s13, s13, s12
	s_mul_hi_u32 s12, s11, s13
	s_mul_i32 s13, s12, s10
	s_sub_i32 s11, s11, s13
	s_add_i32 s13, s12, 1
	s_sub_i32 s14, s11, s10
	s_cmp_ge_u32 s11, s10
	s_cselect_b32 s12, s13, s12
	s_cselect_b32 s11, s14, s11
	s_add_i32 s13, s12, 1
	s_cmp_ge_u32 s11, s10
	s_cselect_b32 s10, s13, s12
	s_xor_b32 s10, s10, s0
	s_sub_i32 s0, s10, s0
	s_mul_i32 s9, s0, s9
	s_sub_i32 s1, s1, s9
	s_add_i32 s8, s8, s1
	s_ashr_i32 s9, s8, 31
	s_lshl_b64 s[10:11], s[8:9], 18
	s_add_u32 s9, s41, s10
	s_addc_u32 s22, s42, s11
	s_ashr_i32 s1, s0, 31
	s_lshl_b64 s[12:13], s[0:1], 18
	s_add_u32 s1, s33, s12
	s_addc_u32 s23, s40, s13
	v_readlane_b32 s40, v252, 42
	v_readlane_b32 s54, v252, 56
	v_readlane_b32 s55, v252, 57
	s_add_u32 s10, s54, s10
	v_pk_mul_f32 v[8:9], v[8:9], v[138:139]
	s_addc_u32 s11, s55, s11
	v_lshlrev_b32_e32 v138, 7, v0
	v_lshlrev_b32_e32 v141, 3, v205
	v_and_b32_e32 v138, 0xc000, v138
	v_lshlrev_b32_e32 v140, 10, v206
	v_and_b32_e32 v141, 0x1c000, v141
	s_add_u32 s12, s54, s12
	v_mov_b32_e32 v135, 0
	v_or3_b32 v138, v179, v138, v140
	v_or3_b32 v140, v179, v141, v140
	s_addc_u32 s13, s55, s13
	v_readlane_b32 s43, v252, 45
	v_readlane_b32 s45, v252, 47
	v_readlane_b32 s48, v252, 50
	v_readlane_b32 s52, v252, 54
	v_add_u32_e32 v138, v138, v204
	v_mov_b32_e32 v139, v135
	v_add_u32_e32 v140, v140, v204
	v_mov_b32_e32 v141, v135
	s_add_u32 s24, s12, 0x1800100
	v_readlane_b32 s41, v252, 43
	v_readlane_b32 s42, v252, 44
	v_readlane_b32 s44, v252, 46
	v_readlane_b32 s46, v252, 48
	v_readlane_b32 s47, v252, 49
	v_readlane_b32 s49, v252, 51
	v_readlane_b32 s53, v252, 55
	v_lshl_add_u64 v[138:139], s[10:11], 0, v[138:139]
	s_mov_b64 s[14:15], 0x1ac20080
	v_lshl_add_u64 v[140:141], s[10:11], 0, v[140:141]
	s_addc_u32 s25, s13, 0
	s_add_i32 s31, s16, 0
	s_add_i32 s43, s26, s16
	s_add_i32 s45, s27, s16
	s_add_i32 s48, s28, s16
	s_add_i32 s52, s29, s16
	v_lshl_or_b32 v208, s21, 7, v208
	v_mov_b32_e32 v137, v135
	v_lshl_add_u64 v[138:139], v[138:139], 0, s[14:15]
	v_lshl_add_u64 v[140:141], v[140:141], 0, s[14:15]
	s_mov_b32 s30, -2
	s_mov_b64 s[12:13], 0
	v_add_u32_e32 v142, 0, v209
	s_add_i32 s33, s31, 0xe000
	s_add_i32 s34, s31, 0x4000
	s_add_i32 s35, s31, 0x6000
	s_mov_b64 s[14:15], 0x80
	s_add_i32 s40, s31, 0x8000
	s_add_i32 s41, s31, 0xa000
	s_add_i32 s42, s31, 0xc000
	s_add_i32 s44, s43, 0x2000
	s_add_i32 s46, s45, 0x2000
	s_add_i32 s47, s31, 0x2000
	s_add_i32 s49, s48, 0x2000
	s_add_i32 s53, s52, 0x2000
	v_readlane_b32 s50, v252, 52
	v_readlane_b32 s51, v252, 53

.LBB0_1237:
	v_lshl_add_u32 v130, s8, 8, v207
	v_ashrrev_i32_e32 v131, 31, v130
	s_lshl_b32 s0, s0, 8
	v_lshlrev_b64 v[130:131], 10, v[130:131]
	s_ashr_i32 s1, s0, 31
	v_lshl_add_u64 v[138:139], v[130:131], 0, s[0:1]
	v_or3_b32 v138, s21, v1, v138
	v_bfe_u32 v254, v138, 5, 5
	v_bfe_u32 v255, v138, 10, 4
	v_and_b32_e32 v130, 0xffffc01f, v138
	v_lshl_or_b32 v130, v254, 9, v130
	v_lshl_or_b32 v130, v255, 5, v130
	v_mov_b32_e32 v131, v139
	v_lshl_add_u64 v[130:131], s[6:7], 0, v[130:131]
	v_add_co_u32_e32 v132, vcc, 0x4000, v130
	s_mov_b32 s0, 0x8000
	s_nop 0
	v_addc_co_u32_e32 v133, vcc, 0, v131, vcc
	global_load_dwordx2 v[140:141], v[130:131], off
	global_load_dwordx2 v[142:143], v[130:131], off offset:2048
	global_load_dwordx2 v[144:145], v[132:133], off
	global_load_dwordx2 v[146:147], v[132:133], off offset:2048
	v_add_co_u32_e32 v132, vcc, 0x8000, v130
	s_nop 1
	v_addc_co_u32_e32 v133, vcc, 0, v131, vcc
	v_add_co_u32_e32 v148, vcc, 0xc000, v130
	s_nop 1
	v_addc_co_u32_e32 v149, vcc, 0, v131, vcc
	global_load_dwordx2 v[150:151], v[132:133], off
	global_load_dwordx2 v[136:137], v[132:133], off offset:2048
	global_load_dwordx2 v[134:135], v[148:149], off
	s_nop 0
	global_load_dwordx2 v[132:133], v[148:149], off offset:2048
	s_mov_b32 s99, 0
	s_mov_b32 s98, 0x20000
	v_lshl_add_u64 v[224:225], v[130:131], 0, s[98:99]
	s_mov_b32 s98, 0x24000
	v_lshl_add_u64 v[226:227], v[130:131], 0, s[98:99]
	s_mov_b32 s98, 0x28000
	v_lshl_add_u64 v[228:229], v[130:131], 0, s[98:99]
	s_mov_b32 s98, 0x2c000
	v_lshl_add_u64 v[230:231], v[130:131], 0, s[98:99]
	global_load_dwordx2 v[232:233], v[224:225], off
	global_load_dwordx2 v[234:235], v[224:225], off offset:2048
	global_load_dwordx2 v[236:237], v[226:227], off
	global_load_dwordx2 v[238:239], v[226:227], off offset:2048
	global_load_dwordx2 v[240:241], v[228:229], off
	global_load_dwordx2 v[242:243], v[228:229], off offset:2048
	global_load_dwordx2 v[244:245], v[230:231], off
	global_load_dwordx2 v[246:247], v[230:231], off offset:2048
	s_waitcnt vmcnt(0)
	v_cvt_f32_ubyte1_e32 v148, v140
	v_cvt_f32_ubyte0_e32 v1, v140
	v_mul_f32_e32 v149, 0x3b808081, v148
	v_cvt_f32_ubyte2_e32 v148, v140
	v_cvt_f32_ubyte3_e32 v140, v140
	v_mul_f32_e32 v153, 0x3b808081, v140
	v_cvt_f32_ubyte0_e32 v140, v141
	v_mul_f32_e32 v152, 0x3b808081, v148
	v_mul_f32_e32 v148, 0x3b808081, v140
	v_cvt_f32_ubyte1_e32 v140, v141
	v_mul_f32_e32 v154, 0x3b808081, v140
	v_cvt_f32_ubyte2_e32 v140, v141
	v_mul_f32_e32 v1, 0x3b808081, v1
	v_mul_f32_e32 v155, 0x3b808081, v140
	v_cvt_f32_ubyte3_e32 v140, v141
	v_mul_f32_e32 v156, 0x3b808081, v140
	v_max_f32_e32 v140, 0x3b008081, v1
	v_max_f32_e32 v148, 0x3b008081, v148
	v_max_f32_e32 v141, 0x3b008081, v149
	v_max_f32_e32 v149, 0x3b008081, v154
	v_pk_mul_f32 v[66:67], v[66:67], v[140:141]
	v_pk_mul_f32 v[140:141], v[74:75], v[148:149]
	v_max_f32_e32 v74, 0x3b008081, v152
	v_max_f32_e32 v75, 0x3b008081, v153
	v_pk_mul_f32 v[68:69], v[68:69], v[74:75]
	v_max_f32_e32 v148, 0x3b008081, v155
	v_cvt_pk_bf16_f32 v75, v68, v69
	v_cvt_f32_ubyte1_e32 v68, v142
	v_max_f32_e32 v149, 0x3b008081, v156
	v_mul_f32_e32 v69, 0x3b808081, v68
	v_cvt_f32_ubyte2_e32 v68, v142
	v_pk_mul_f32 v[148:149], v[76:77], v[148:149]
	v_cvt_pk_bf16_f32 v74, v66, v67
	v_lshl_add_u64 v[66:67], v[138:139], 1, s[4:5]
	v_mul_f32_e32 v138, 0x3b808081, v68
	v_cvt_f32_ubyte3_e32 v68, v142
	v_cvt_pk_bf16_f32 v76, v140, v141
	v_cvt_pk_bf16_f32 v77, v148, v149
	v_mul_f32_e32 v139, 0x3b808081, v68
	v_cvt_f32_ubyte0_e32 v68, v143
	global_store_dwordx4 v[66:67], v[74:77], off
	v_cvt_f32_ubyte0_e32 v1, v142
	v_mul_f32_e32 v1, 0x3b808081, v1
	v_mul_f32_e32 v74, 0x3b808081, v68
	v_cvt_f32_ubyte1_e32 v68, v143
	v_mul_f32_e32 v75, 0x3b808081, v68
	v_cvt_f32_ubyte2_e32 v68, v143
	v_mul_f32_e32 v140, 0x3b808081, v68
	v_cvt_f32_ubyte3_e32 v68, v143
	v_mul_f32_e32 v141, 0x3b808081, v68
	v_max_f32_e32 v68, 0x3b008081, v1
	v_max_f32_e32 v74, 0x3b008081, v74
	v_max_f32_e32 v69, 0x3b008081, v69
	v_max_f32_e32 v75, 0x3b008081, v75
	v_pk_mul_f32 v[68:69], v[78:79], v[68:69]
	v_pk_mul_f32 v[76:77], v[86:87], v[74:75]
	v_max_f32_e32 v74, 0x3b008081, v138
	v_max_f32_e32 v75, 0x3b008081, v139
	v_max_f32_e32 v78, 0x3b008081, v140
	v_pk_mul_f32 v[80:81], v[80:81], v[74:75]
	v_max_f32_e32 v79, 0x3b008081, v141
	v_cvt_pk_bf16_f32 v74, v68, v69
	v_cvt_f32_ubyte1_e32 v68, v144
	v_pk_mul_f32 v[78:79], v[88:89], v[78:79]
	v_mul_f32_e32 v69, 0x3b808081, v68
	v_cvt_f32_ubyte2_e32 v68, v144
	v_cvt_pk_bf16_f32 v76, v76, v77
	v_cvt_pk_bf16_f32 v77, v78, v79
	v_mul_f32_e32 v78, 0x3b808081, v68
	v_cvt_f32_ubyte3_e32 v68, v144
	v_cvt_pk_bf16_f32 v75, v80, v81
	v_mul_f32_e32 v79, 0x3b808081, v68
	v_cvt_f32_ubyte0_e32 v68, v145
	global_store_dwordx4 v[66:67], v[74:77], off offset:256
	v_cvt_f32_ubyte0_e32 v1, v144
	v_mul_f32_e32 v1, 0x3b808081, v1
	v_mul_f32_e32 v74, 0x3b808081, v68
	v_cvt_f32_ubyte1_e32 v68, v145
	v_mul_f32_e32 v75, 0x3b808081, v68
	v_cvt_f32_ubyte2_e32 v68, v145
	v_mul_f32_e32 v80, 0x3b808081, v68
	v_cvt_f32_ubyte3_e32 v68, v145
	v_mul_f32_e32 v86, 0x3b808081, v68
	v_max_f32_e32 v68, 0x3b008081, v1
	v_max_f32_e32 v74, 0x3b008081, v74
	v_max_f32_e32 v69, 0x3b008081, v69
	v_max_f32_e32 v75, 0x3b008081, v75
	v_pk_mul_f32 v[68:69], v[90:91], v[68:69]
	v_pk_mul_f32 v[76:77], v[94:95], v[74:75]
	v_max_f32_e32 v74, 0x3b008081, v78
	v_max_f32_e32 v78, 0x3b008081, v80
	v_max_f32_e32 v75, 0x3b008081, v79
	v_max_f32_e32 v79, 0x3b008081, v86
	v_pk_mul_f32 v[80:81], v[92:93], v[74:75]
	v_pk_mul_f32 v[78:79], v[96:97], v[78:79]
	v_cvt_pk_bf16_f32 v74, v68, v69
	v_add_co_u32_e32 v68, vcc, s0, v66
	v_cvt_pk_bf16_f32 v75, v80, v81
	v_cvt_pk_bf16_f32 v76, v76, v77
	v_cvt_pk_bf16_f32 v77, v78, v79
	v_addc_co_u32_e32 v69, vcc, 0, v67, vcc
	global_store_dwordx4 v[68:69], v[74:77], off
	v_cvt_f32_ubyte0_e32 v1, v146
	v_mul_f32_e32 v1, 0x3b808081, v1
	v_cvt_f32_ubyte1_e32 v74, v146
	v_mul_f32_e32 v75, 0x3b808081, v74
	v_cvt_f32_ubyte2_e32 v74, v146
	v_mul_f32_e32 v78, 0x3b808081, v74
	v_cvt_f32_ubyte3_e32 v74, v146
	v_mul_f32_e32 v79, 0x3b808081, v74
	v_cvt_f32_ubyte0_e32 v74, v147
	v_mul_f32_e32 v76, 0x3b808081, v74
	v_cvt_f32_ubyte1_e32 v74, v147
	v_mul_f32_e32 v77, 0x3b808081, v74
	v_cvt_f32_ubyte2_e32 v74, v147
	v_mul_f32_e32 v80, 0x3b808081, v74
	v_cvt_f32_ubyte3_e32 v74, v147
	v_mul_f32_e32 v81, 0x3b808081, v74
	v_max_f32_e32 v74, 0x3b008081, v1
	v_max_f32_e32 v76, 0x3b008081, v76
	v_max_f32_e32 v75, 0x3b008081, v75
	v_max_f32_e32 v77, 0x3b008081, v77
	v_max_f32_e32 v78, 0x3b008081, v78
	v_max_f32_e32 v80, 0x3b008081, v80
	v_max_f32_e32 v79, 0x3b008081, v79
	v_max_f32_e32 v81, 0x3b008081, v81
	v_pk_mul_f32 v[74:75], v[98:99], v[74:75]
	v_pk_mul_f32 v[76:77], v[102:103], v[76:77]
	v_pk_mul_f32 v[78:79], v[100:101], v[78:79]
	v_pk_mul_f32 v[80:81], v[104:105], v[80:81]
	v_cvt_pk_bf16_f32 v74, v74, v75
	v_cvt_pk_bf16_f32 v75, v78, v79
	v_cvt_pk_bf16_f32 v76, v76, v77
	v_cvt_pk_bf16_f32 v77, v80, v81
	global_store_dwordx4 v[68:69], v[74:77], off offset:256
	v_cvt_f32_ubyte1_e32 v68, v150
	v_mul_f32_e32 v69, 0x3b808081, v68
	v_cvt_f32_ubyte2_e32 v68, v150
	v_mul_f32_e32 v78, 0x3b808081, v68
	v_cvt_f32_ubyte3_e32 v68, v150
	v_mul_f32_e32 v79, 0x3b808081, v68
	v_cvt_f32_ubyte0_e32 v68, v151
	v_mul_f32_e32 v74, 0x3b808081, v68
	v_cvt_f32_ubyte1_e32 v68, v151
	v_cvt_f32_ubyte0_e32 v1, v150
	v_mul_f32_e32 v75, 0x3b808081, v68
	v_cvt_f32_ubyte2_e32 v68, v151
	v_mul_f32_e32 v1, 0x3b808081, v1
	v_mul_f32_e32 v80, 0x3b808081, v68
	v_cvt_f32_ubyte3_e32 v68, v151
	v_mul_f32_e32 v86, 0x3b808081, v68
	v_max_f32_e32 v68, 0x3b008081, v1
	v_max_f32_e32 v74, 0x3b008081, v74
	v_max_f32_e32 v69, 0x3b008081, v69
	v_max_f32_e32 v75, 0x3b008081, v75
	v_pk_mul_f32 v[68:69], v[110:111], v[68:69]
	v_pk_mul_f32 v[76:77], v[118:119], v[74:75]
	v_max_f32_e32 v74, 0x3b008081, v78
	v_max_f32_e32 v78, 0x3b008081, v80
	v_max_f32_e32 v75, 0x3b008081, v79
	v_max_f32_e32 v79, 0x3b008081, v86
	s_mov_b32 s0, 0x10000
	v_pk_mul_f32 v[80:81], v[112:113], v[74:75]
	v_pk_mul_f32 v[78:79], v[120:121], v[78:79]
	v_cvt_pk_bf16_f32 v74, v68, v69
	v_add_co_u32_e32 v68, vcc, s0, v66
	v_cvt_pk_bf16_f32 v75, v80, v81
	v_cvt_pk_bf16_f32 v76, v76, v77
	v_cvt_pk_bf16_f32 v77, v78, v79
	v_addc_co_u32_e32 v69, vcc, 0, v67, vcc
	global_store_dwordx4 v[68:69], v[74:77], off
	v_cvt_f32_ubyte0_e32 v1, v136
	v_mul_f32_e32 v1, 0x3b808081, v1
	v_cvt_f32_ubyte1_e32 v74, v136
	v_mul_f32_e32 v75, 0x3b808081, v74
	v_cvt_f32_ubyte2_e32 v74, v136
	v_mul_f32_e32 v78, 0x3b808081, v74
	v_cvt_f32_ubyte3_e32 v74, v136
	v_mul_f32_e32 v79, 0x3b808081, v74
	v_cvt_f32_ubyte0_e32 v74, v137
	v_mul_f32_e32 v76, 0x3b808081, v74
	v_cvt_f32_ubyte1_e32 v74, v137
	v_mul_f32_e32 v77, 0x3b808081, v74
	v_cvt_f32_ubyte2_e32 v74, v137
	v_mul_f32_e32 v80, 0x3b808081, v74
	v_cvt_f32_ubyte3_e32 v74, v137
	v_mul_f32_e32 v81, 0x3b808081, v74
	v_max_f32_e32 v74, 0x3b008081, v1
	v_max_f32_e32 v76, 0x3b008081, v76
	v_max_f32_e32 v75, 0x3b008081, v75
	v_max_f32_e32 v77, 0x3b008081, v77
	v_max_f32_e32 v78, 0x3b008081, v78
	v_max_f32_e32 v80, 0x3b008081, v80
	v_max_f32_e32 v79, 0x3b008081, v79
	v_max_f32_e32 v81, 0x3b008081, v81
	v_pk_mul_f32 v[74:75], v[122:123], v[74:75]
	v_pk_mul_f32 v[76:77], v[126:127], v[76:77]
	v_pk_mul_f32 v[78:79], v[124:125], v[78:79]
	v_pk_mul_f32 v[80:81], v[128:129], v[80:81]
	v_cvt_pk_bf16_f32 v74, v74, v75
	v_cvt_pk_bf16_f32 v75, v78, v79
	v_cvt_pk_bf16_f32 v76, v76, v77
	v_cvt_pk_bf16_f32 v77, v80, v81
	global_store_dwordx4 v[68:69], v[74:77], off offset:256
	v_cvt_f32_ubyte1_e32 v68, v134
	v_mul_f32_e32 v69, 0x3b808081, v68
	v_cvt_f32_ubyte2_e32 v68, v134
	v_mul_f32_e32 v78, 0x3b808081, v68
	v_cvt_f32_ubyte3_e32 v68, v134
	v_mul_f32_e32 v79, 0x3b808081, v68
	v_cvt_f32_ubyte0_e32 v68, v135
	v_mul_f32_e32 v74, 0x3b808081, v68
	v_cvt_f32_ubyte1_e32 v68, v135
	v_mul_f32_e32 v75, 0x3b808081, v68
	v_cvt_f32_ubyte2_e32 v68, v135
	v_cvt_f32_ubyte0_e32 v1, v134
	v_mul_f32_e32 v80, 0x3b808081, v68
	v_cvt_f32_ubyte3_e32 v68, v135
	v_mul_f32_e32 v1, 0x3b808081, v1
	v_mul_f32_e32 v86, 0x3b808081, v68
	v_max_f32_e32 v74, 0x3b008081, v74
	v_max_f32_e32 v75, 0x3b008081, v75
	v_max_f32_e32 v68, 0x3b008081, v1
	v_max_f32_e32 v69, 0x3b008081, v69
	v_pk_mul_f32 v[76:77], v[106:107], v[74:75]
	v_max_f32_e32 v74, 0x3b008081, v78
	v_max_f32_e32 v78, 0x3b008081, v80
	v_max_f32_e32 v75, 0x3b008081, v79
	v_max_f32_e32 v79, 0x3b008081, v86
	v_pk_mul_f32 v[68:69], v[114:115], v[68:69]
	v_pk_mul_f32 v[78:79], v[108:109], v[78:79]
	s_mov_b32 s0, 0x18000
	v_pk_mul_f32 v[80:81], v[116:117], v[74:75]
	v_cvt_pk_bf16_f32 v74, v68, v69
	v_cvt_pk_bf16_f32 v76, v76, v77
	v_cvt_pk_bf16_f32 v77, v78, v79
	v_add_co_u32_e32 v78, vcc, s0, v66
	v_cvt_f32_ubyte1_e32 v68, v132
	v_cvt_pk_bf16_f32 v75, v80, v81
	v_addc_co_u32_e32 v79, vcc, 0, v67, vcc
	v_mul_f32_e32 v69, 0x3b808081, v68
	v_cvt_f32_ubyte2_e32 v68, v132
	global_store_dwordx4 v[78:79], v[74:77], off
	v_cvt_f32_ubyte0_e32 v1, v132
	v_mul_f32_e32 v1, 0x3b808081, v1
	v_mul_f32_e32 v76, 0x3b808081, v68
	v_cvt_f32_ubyte3_e32 v68, v132
	v_mul_f32_e32 v77, 0x3b808081, v68
	v_cvt_f32_ubyte0_e32 v68, v133
	v_mul_f32_e32 v74, 0x3b808081, v68
	v_cvt_f32_ubyte1_e32 v68, v133
	v_mul_f32_e32 v75, 0x3b808081, v68
	v_cvt_f32_ubyte2_e32 v68, v133
	v_mul_f32_e32 v80, 0x3b808081, v68
	v_cvt_f32_ubyte3_e32 v68, v133
	v_mul_f32_e32 v81, 0x3b808081, v68
	v_max_f32_e32 v74, 0x3b008081, v74
	v_max_f32_e32 v75, 0x3b008081, v75
	v_max_f32_e32 v68, 0x3b008081, v1
	v_max_f32_e32 v69, 0x3b008081, v69
	v_pk_mul_f32 v[70:71], v[70:71], v[74:75]
	v_max_f32_e32 v74, 0x3b008081, v76
	v_max_f32_e32 v76, 0x3b008081, v80
	v_max_f32_e32 v75, 0x3b008081, v77
	v_max_f32_e32 v77, 0x3b008081, v81
	v_pk_mul_f32 v[68:69], v[82:83], v[68:69]
	v_pk_mul_f32 v[74:75], v[84:85], v[74:75]
	v_pk_mul_f32 v[72:73], v[72:73], v[76:77]
	v_cvt_pk_bf16_f32 v68, v68, v69
	v_cvt_pk_bf16_f32 v69, v74, v75
	v_cvt_pk_bf16_f32 v70, v70, v71
	v_cvt_pk_bf16_f32 v71, v72, v73
	global_store_dwordx4 v[78:79], v[68:71], off offset:256
	s_mov_b32 s0, 0x20000
	s_nop 0
	s_mov_b32 s0, 0x24000
	s_nop 0
	s_mov_b32 s0, 0x28000
	s_nop 0
	s_mov_b32 s0, 0x2c000
	s_nop 0
	v_mov_b32_e32 v74, v232
	v_mov_b32_e32 v75, v233
	v_mov_b32_e32 v76, v234
	v_mov_b32_e32 v77, v235
	v_mov_b32_e32 v78, v236
	v_mov_b32_e32 v79, v237
	v_mov_b32_e32 v80, v238
	v_mov_b32_e32 v81, v239
	v_mov_b32_e32 v86, v240
	v_mov_b32_e32 v87, v241
	v_mov_b32_e32 v72, v242
	v_mov_b32_e32 v73, v243
	v_mov_b32_e32 v70, v244
	v_mov_b32_e32 v71, v245
	v_mov_b32_e32 v68, v246
	v_mov_b32_e32 v69, v247
	s_waitcnt vmcnt(7)
	v_cvt_f32_ubyte1_e32 v82, v74
	v_cvt_f32_ubyte0_e32 v1, v74
	v_mul_f32_e32 v83, 0x3b808081, v82
	v_cvt_f32_ubyte2_e32 v82, v74
	v_cvt_f32_ubyte3_e32 v74, v74
	v_mul_f32_e32 v85, 0x3b808081, v74
	v_cvt_f32_ubyte0_e32 v74, v75
	v_mul_f32_e32 v84, 0x3b808081, v82
	v_mul_f32_e32 v82, 0x3b808081, v74
	v_cvt_f32_ubyte1_e32 v74, v75
	v_mul_f32_e32 v88, 0x3b808081, v74
	v_cvt_f32_ubyte2_e32 v74, v75
	v_mul_f32_e32 v1, 0x3b808081, v1
	v_mul_f32_e32 v89, 0x3b808081, v74
	v_cvt_f32_ubyte3_e32 v74, v75
	v_mul_f32_e32 v90, 0x3b808081, v74
	v_max_f32_e32 v74, 0x3b008081, v1
	v_max_f32_e32 v82, 0x3b008081, v82
	v_max_f32_e32 v75, 0x3b008081, v83
	v_max_f32_e32 v83, 0x3b008081, v88
	v_pk_mul_f32 v[62:63], v[62:63], v[74:75]
	v_pk_mul_f32 v[74:75], v[58:59], v[82:83]
	v_max_f32_e32 v58, 0x3b008081, v84
	v_max_f32_e32 v82, 0x3b008081, v89
	v_max_f32_e32 v59, 0x3b008081, v85
	v_max_f32_e32 v83, 0x3b008081, v90
	s_mov_b32 s0, 0x40000
	v_pk_mul_f32 v[64:65], v[64:65], v[58:59]
	v_pk_mul_f32 v[82:83], v[60:61], v[82:83]
	v_cvt_pk_bf16_f32 v58, v62, v63
	v_add_co_u32_e32 v62, vcc, s0, v66
	v_cvt_pk_bf16_f32 v59, v64, v65
	v_cvt_pk_bf16_f32 v60, v74, v75
	v_cvt_pk_bf16_f32 v61, v82, v83
	v_addc_co_u32_e32 v63, vcc, 0, v67, vcc
	global_store_dwordx4 v[62:63], v[58:61], off
	s_waitcnt vmcnt(7)
	v_cvt_f32_ubyte0_e32 v1, v76
	v_mul_f32_e32 v1, 0x3b808081, v1
	v_cvt_f32_ubyte1_e32 v58, v76
	v_mul_f32_e32 v59, 0x3b808081, v58
	v_cvt_f32_ubyte2_e32 v58, v76
	v_mul_f32_e32 v64, 0x3b808081, v58
	v_cvt_f32_ubyte3_e32 v58, v76
	v_mul_f32_e32 v65, 0x3b808081, v58
	v_cvt_f32_ubyte0_e32 v58, v77
	v_mul_f32_e32 v60, 0x3b808081, v58
	v_cvt_f32_ubyte1_e32 v58, v77
	v_mul_f32_e32 v61, 0x3b808081, v58
	v_cvt_f32_ubyte2_e32 v58, v77
	v_mul_f32_e32 v74, 0x3b808081, v58
	v_cvt_f32_ubyte3_e32 v58, v77
	v_mul_f32_e32 v75, 0x3b808081, v58
	v_max_f32_e32 v58, 0x3b008081, v1
	v_max_f32_e32 v60, 0x3b008081, v60
	v_max_f32_e32 v59, 0x3b008081, v59
	v_max_f32_e32 v61, 0x3b008081, v61
	v_pk_mul_f32 v[54:55], v[54:55], v[58:59]
	v_pk_mul_f32 v[58:59], v[50:51], v[60:61]
	v_max_f32_e32 v50, 0x3b008081, v64
	v_max_f32_e32 v60, 0x3b008081, v74
	v_max_f32_e32 v51, 0x3b008081, v65
	v_max_f32_e32 v61, 0x3b008081, v75
	v_pk_mul_f32 v[56:57], v[56:57], v[50:51]
	v_pk_mul_f32 v[60:61], v[52:53], v[60:61]
	v_cvt_pk_bf16_f32 v50, v54, v55
	v_cvt_pk_bf16_f32 v51, v56, v57
	v_cvt_pk_bf16_f32 v52, v58, v59
	v_cvt_pk_bf16_f32 v53, v60, v61
	global_store_dwordx4 v[62:63], v[50:53], off offset:256
	s_waitcnt vmcnt(7)
	v_cvt_f32_ubyte0_e32 v1, v78
	v_mul_f32_e32 v1, 0x3b808081, v1
	v_cvt_f32_ubyte1_e32 v50, v78
	v_mul_f32_e32 v51, 0x3b808081, v50
	v_cvt_f32_ubyte2_e32 v50, v78
	v_mul_f32_e32 v54, 0x3b808081, v50
	v_cvt_f32_ubyte3_e32 v50, v78
	v_mul_f32_e32 v55, 0x3b808081, v50
	v_cvt_f32_ubyte0_e32 v50, v79
	v_mul_f32_e32 v52, 0x3b808081, v50
	v_cvt_f32_ubyte1_e32 v50, v79
	v_mul_f32_e32 v53, 0x3b808081, v50
	v_cvt_f32_ubyte2_e32 v50, v79
	v_mul_f32_e32 v56, 0x3b808081, v50
	v_cvt_f32_ubyte3_e32 v50, v79
	v_mul_f32_e32 v57, 0x3b808081, v50
	v_max_f32_e32 v50, 0x3b008081, v1
	v_max_f32_e32 v52, 0x3b008081, v52
	v_max_f32_e32 v51, 0x3b008081, v51
	v_max_f32_e32 v53, 0x3b008081, v53
	v_pk_mul_f32 v[46:47], v[46:47], v[50:51]
	v_pk_mul_f32 v[50:51], v[42:43], v[52:53]
	v_max_f32_e32 v42, 0x3b008081, v54
	v_max_f32_e32 v52, 0x3b008081, v56
	v_max_f32_e32 v43, 0x3b008081, v55
	v_max_f32_e32 v53, 0x3b008081, v57
	s_mov_b32 s0, 0x48000
	v_pk_mul_f32 v[48:49], v[48:49], v[42:43]
	v_pk_mul_f32 v[52:53], v[44:45], v[52:53]
	v_cvt_pk_bf16_f32 v42, v46, v47
	v_add_co_u32_e32 v46, vcc, s0, v66
	v_cvt_pk_bf16_f32 v43, v48, v49
	v_cvt_pk_bf16_f32 v44, v50, v51
	v_cvt_pk_bf16_f32 v45, v52, v53
	v_addc_co_u32_e32 v47, vcc, 0, v67, vcc
	global_store_dwordx4 v[46:47], v[42:45], off
	s_waitcnt vmcnt(7)
	v_cvt_f32_ubyte0_e32 v1, v80
	v_mul_f32_e32 v1, 0x3b808081, v1
	v_cvt_f32_ubyte1_e32 v42, v80
	v_mul_f32_e32 v43, 0x3b808081, v42
	v_cvt_f32_ubyte2_e32 v42, v80
	v_mul_f32_e32 v48, 0x3b808081, v42
	v_cvt_f32_ubyte3_e32 v42, v80
	v_mul_f32_e32 v49, 0x3b808081, v42
	v_cvt_f32_ubyte0_e32 v42, v81
	v_mul_f32_e32 v44, 0x3b808081, v42
	v_cvt_f32_ubyte1_e32 v42, v81
	v_mul_f32_e32 v45, 0x3b808081, v42
	v_cvt_f32_ubyte2_e32 v42, v81
	v_mul_f32_e32 v50, 0x3b808081, v42
	v_cvt_f32_ubyte3_e32 v42, v81
	v_mul_f32_e32 v51, 0x3b808081, v42
	v_max_f32_e32 v42, 0x3b008081, v1
	v_max_f32_e32 v44, 0x3b008081, v44
	v_max_f32_e32 v43, 0x3b008081, v43
	v_max_f32_e32 v45, 0x3b008081, v45
	v_pk_mul_f32 v[38:39], v[38:39], v[42:43]
	v_pk_mul_f32 v[42:43], v[34:35], v[44:45]
	v_max_f32_e32 v34, 0x3b008081, v48
	v_max_f32_e32 v44, 0x3b008081, v50
	v_max_f32_e32 v35, 0x3b008081, v49
	v_max_f32_e32 v45, 0x3b008081, v51
	v_pk_mul_f32 v[40:41], v[40:41], v[34:35]
	v_pk_mul_f32 v[44:45], v[36:37], v[44:45]
	v_cvt_pk_bf16_f32 v34, v38, v39
	v_cvt_pk_bf16_f32 v35, v40, v41
	v_cvt_pk_bf16_f32 v36, v42, v43
	v_cvt_pk_bf16_f32 v37, v44, v45
	global_store_dwordx4 v[46:47], v[34:37], off offset:256
	s_waitcnt vmcnt(7)
	v_cvt_f32_ubyte0_e32 v1, v86
	v_mul_f32_e32 v1, 0x3b808081, v1
	v_cvt_f32_ubyte1_e32 v34, v86
	v_mul_f32_e32 v35, 0x3b808081, v34
	v_cvt_f32_ubyte2_e32 v34, v86
	v_mul_f32_e32 v38, 0x3b808081, v34
	v_cvt_f32_ubyte3_e32 v34, v86
	v_mul_f32_e32 v39, 0x3b808081, v34
	v_cvt_f32_ubyte0_e32 v34, v87
	v_mul_f32_e32 v36, 0x3b808081, v34
	v_cvt_f32_ubyte1_e32 v34, v87
	v_mul_f32_e32 v37, 0x3b808081, v34
	v_cvt_f32_ubyte2_e32 v34, v87
	v_mul_f32_e32 v40, 0x3b808081, v34
	v_cvt_f32_ubyte3_e32 v34, v87
	v_mul_f32_e32 v41, 0x3b808081, v34
	v_max_f32_e32 v34, 0x3b008081, v1
	v_max_f32_e32 v36, 0x3b008081, v36
	v_max_f32_e32 v35, 0x3b008081, v35
	v_max_f32_e32 v37, 0x3b008081, v37
	v_pk_mul_f32 v[26:27], v[26:27], v[34:35]
	v_pk_mul_f32 v[34:35], v[18:19], v[36:37]
	v_max_f32_e32 v18, 0x3b008081, v38
	v_max_f32_e32 v36, 0x3b008081, v40
	v_max_f32_e32 v19, 0x3b008081, v39
	v_max_f32_e32 v37, 0x3b008081, v41
	s_mov_b32 s0, 0x50000
	v_pk_mul_f32 v[28:29], v[28:29], v[18:19]
	v_pk_mul_f32 v[36:37], v[20:21], v[36:37]
	v_cvt_pk_bf16_f32 v18, v26, v27
	v_add_co_u32_e32 v26, vcc, s0, v66
	v_cvt_pk_bf16_f32 v19, v28, v29
	v_cvt_pk_bf16_f32 v20, v34, v35
	v_cvt_pk_bf16_f32 v21, v36, v37
	v_addc_co_u32_e32 v27, vcc, 0, v67, vcc
	global_store_dwordx4 v[26:27], v[18:21], off
	s_waitcnt vmcnt(7)
	v_cvt_f32_ubyte0_e32 v1, v72
	v_mul_f32_e32 v1, 0x3b808081, v1
	v_cvt_f32_ubyte1_e32 v18, v72
	v_mul_f32_e32 v19, 0x3b808081, v18
	v_cvt_f32_ubyte2_e32 v18, v72
	v_mul_f32_e32 v28, 0x3b808081, v18
	v_cvt_f32_ubyte3_e32 v18, v72
	v_mul_f32_e32 v29, 0x3b808081, v18
	v_cvt_f32_ubyte0_e32 v18, v73
	v_mul_f32_e32 v20, 0x3b808081, v18
	v_cvt_f32_ubyte1_e32 v18, v73
	v_mul_f32_e32 v21, 0x3b808081, v18
	v_cvt_f32_ubyte2_e32 v18, v73
	v_mul_f32_e32 v34, 0x3b808081, v18
	v_cvt_f32_ubyte3_e32 v18, v73
	v_mul_f32_e32 v35, 0x3b808081, v18
	v_max_f32_e32 v20, 0x3b008081, v20
	v_max_f32_e32 v21, 0x3b008081, v21
	v_max_f32_e32 v18, 0x3b008081, v1
	v_max_f32_e32 v19, 0x3b008081, v19
	v_pk_mul_f32 v[20:21], v[22:23], v[20:21]
	v_max_f32_e32 v22, 0x3b008081, v28
	v_max_f32_e32 v28, 0x3b008081, v34
	v_max_f32_e32 v23, 0x3b008081, v29
	v_max_f32_e32 v29, 0x3b008081, v35
	v_pk_mul_f32 v[18:19], v[30:31], v[18:19]
	v_pk_mul_f32 v[22:23], v[32:33], v[22:23]
	v_pk_mul_f32 v[24:25], v[24:25], v[28:29]
	v_cvt_pk_bf16_f32 v18, v18, v19
	v_cvt_pk_bf16_f32 v19, v22, v23
	v_cvt_pk_bf16_f32 v20, v20, v21
	v_cvt_pk_bf16_f32 v21, v24, v25
	global_store_dwordx4 v[26:27], v[18:21], off offset:256
	s_waitcnt vmcnt(7)
	v_cvt_f32_ubyte0_e32 v1, v70
	v_mul_f32_e32 v1, 0x3b808081, v1
	v_cvt_f32_ubyte1_e32 v18, v70
	v_mul_f32_e32 v19, 0x3b808081, v18
	v_cvt_f32_ubyte2_e32 v18, v70
	v_mul_f32_e32 v22, 0x3b808081, v18
	v_cvt_f32_ubyte3_e32 v18, v70
	v_mul_f32_e32 v23, 0x3b808081, v18
	v_cvt_f32_ubyte0_e32 v18, v71
	v_mul_f32_e32 v20, 0x3b808081, v18
	v_cvt_f32_ubyte1_e32 v18, v71
	v_mul_f32_e32 v21, 0x3b808081, v18
	v_cvt_f32_ubyte2_e32 v18, v71
	v_mul_f32_e32 v24, 0x3b808081, v18
	v_cvt_f32_ubyte3_e32 v18, v71
	v_mul_f32_e32 v25, 0x3b808081, v18
	v_max_f32_e32 v18, 0x3b008081, v1
	v_max_f32_e32 v20, 0x3b008081, v20
	v_max_f32_e32 v19, 0x3b008081, v19
	v_max_f32_e32 v21, 0x3b008081, v21
	v_pk_mul_f32 v[10:11], v[10:11], v[18:19]
	v_pk_mul_f32 v[18:19], v[2:3], v[20:21]
	v_max_f32_e32 v2, 0x3b008081, v22
	v_max_f32_e32 v20, 0x3b008081, v24
	v_max_f32_e32 v3, 0x3b008081, v23
	v_max_f32_e32 v21, 0x3b008081, v25
	s_mov_b32 s0, 0x58000
	v_pk_mul_f32 v[12:13], v[12:13], v[2:3]
	v_pk_mul_f32 v[20:21], v[4:5], v[20:21]
	v_cvt_pk_bf16_f32 v2, v10, v11
	v_add_co_u32_e32 v10, vcc, s0, v66
	v_cvt_pk_bf16_f32 v3, v12, v13
	v_cvt_pk_bf16_f32 v4, v18, v19
	v_cvt_pk_bf16_f32 v5, v20, v21
	v_addc_co_u32_e32 v11, vcc, 0, v67, vcc
	global_store_dwordx4 v[10:11], v[2:5], off
	s_waitcnt vmcnt(7)
	v_cvt_f32_ubyte0_e32 v1, v68
	v_mul_f32_e32 v1, 0x3b808081, v1
	v_cvt_f32_ubyte1_e32 v2, v68
	v_mul_f32_e32 v3, 0x3b808081, v2
	v_cvt_f32_ubyte2_e32 v2, v68
	v_mul_f32_e32 v12, 0x3b808081, v2
	v_cvt_f32_ubyte3_e32 v2, v68
	v_mul_f32_e32 v13, 0x3b808081, v2
	v_cvt_f32_ubyte0_e32 v2, v69
	v_mul_f32_e32 v4, 0x3b808081, v2
	v_cvt_f32_ubyte1_e32 v2, v69
	v_mul_f32_e32 v5, 0x3b808081, v2
	v_cvt_f32_ubyte2_e32 v2, v69
	v_mul_f32_e32 v18, 0x3b808081, v2
	v_cvt_f32_ubyte3_e32 v2, v69
	v_mul_f32_e32 v19, 0x3b808081, v2
	v_max_f32_e32 v4, 0x3b008081, v4
	v_max_f32_e32 v5, 0x3b008081, v5
	v_max_f32_e32 v2, 0x3b008081, v1
	v_max_f32_e32 v3, 0x3b008081, v3
	v_pk_mul_f32 v[4:5], v[6:7], v[4:5]
	v_max_f32_e32 v6, 0x3b008081, v12
	v_max_f32_e32 v12, 0x3b008081, v18
	v_max_f32_e32 v7, 0x3b008081, v13
	v_max_f32_e32 v13, 0x3b008081, v19
	v_pk_mul_f32 v[2:3], v[14:15], v[2:3]
	v_pk_mul_f32 v[6:7], v[16:17], v[6:7]
	v_pk_mul_f32 v[8:9], v[8:9], v[12:13]
	v_cvt_pk_bf16_f32 v2, v2, v3
	v_cvt_pk_bf16_f32 v3, v6, v7
	v_cvt_pk_bf16_f32 v4, v4, v5
	v_cvt_pk_bf16_f32 v5, v8, v9
	global_store_dwordx4 v[10:11], v[2:5], off offset:256
	s_waitcnt vmcnt(0)
	s_barrier
